# pooling mixer: each wave takes 4 consecutive rows, window rows loaded and unpacked once (4x fewer VALU ops, same add order)
# speedup vs baseline: 1.0130x; 1.0065x over previous
.Lcv_advdone:
	s_cmpk_gt_i32 s0, 0x7ff
	s_cbranch_scc1 .LBB0_403
	s_cmpk_lg_u32 s21, 0x100
	s_cbranch_scc1 .LBB0_364
	v_lshrrev_b32_e32 v246, 6, v1
	s_nop 0
	v_readfirstlane_b32 s6, v246
	s_lshr_b32 s7, s6, 1
	s_lshl_b32 s7, s7, 8
	s_add_u32 s7, s7, s0
	s_sub_u32 s7, s7, 0x400
	s_lshl_b32 s7, s7, 3
	s_and_b32 s12, s6, 1
	s_lshl_b32 s12, s12, 2
	s_add_u32 s12, s12, s7
	s_cmpk_lt_u32 s12, 0x1000
	s_movk_i32 s13, 0x3ff
	s_cselect_b32 s13, 0xff, s13
	s_and_b32 s14, s12, s13
	s_add_u32 s13, s13, 1
	v_and_b32_e32 v244, 63, v1
	v_lshrrev_b32_e32 v245, 4, v244
	v_lshlrev_b32_e64 v245, v245, 1
	v_lshlrev_b32_e32 v244, 4, v244
	s_mov_b32 s8, 0xffff0000
	s_mov_b32 s9, -1
	s_mov_b32 s10, 0
	s_mov_b32 s11, -1
	s_mov_b32 s38, 0
	s_mov_b32 s39, 0xffff0000
	s_add_i32 s15, s14, -8
	s_cmp_lt_u32 s15, s13
	s_cbranch_scc0 .Lp2_ld1
	s_add_i32 s2, s12, -8
	s_mul_i32 s2, s2, 0x3400
	s_add_u32 s2, s2, 0x1800
	v_add_u32_e32 v246, s2, v244
	global_load_dwordx4 v[6:9], v246, s[4:5]
.Lp2_ld1:
	s_add_i32 s15, s14, -7
	s_cmp_lt_u32 s15, s13
	s_cbranch_scc0 .Lp2_ld2
	s_add_i32 s2, s12, -7
	s_mul_i32 s2, s2, 0x3400
	s_add_u32 s2, s2, 0x1800
	v_add_u32_e32 v246, s2, v244
	global_load_dwordx4 v[14:17], v246, s[4:5]
.Lp2_ld2:
	s_add_i32 s15, s14, -6
	s_cmp_lt_u32 s15, s13
	s_cbranch_scc0 .Lp2_ld3
	s_add_i32 s2, s12, -6
	s_mul_i32 s2, s2, 0x3400
	s_add_u32 s2, s2, 0x1800
	v_add_u32_e32 v246, s2, v244
	global_load_dwordx4 v[22:25], v246, s[4:5]
.Lp2_ld3:
	s_add_i32 s15, s14, -5
	s_cmp_lt_u32 s15, s13
	s_cbranch_scc0 .Lp2_ld4
	s_add_i32 s2, s12, -5
	s_mul_i32 s2, s2, 0x3400
	s_add_u32 s2, s2, 0x1800
	v_add_u32_e32 v246, s2, v244
	global_load_dwordx4 v[30:33], v246, s[4:5]
.Lp2_ld4:
	s_add_i32 s15, s14, -4
	s_cmp_lt_u32 s15, s13
	s_cbranch_scc0 .Lp2_ld5
	s_add_i32 s2, s12, -4
	s_mul_i32 s2, s2, 0x3400
	s_add_u32 s2, s2, 0x1800
	v_add_u32_e32 v246, s2, v244
	global_load_dwordx4 v[38:41], v246, s[4:5]
.Lp2_ld5:
	s_add_i32 s15, s14, -3
	s_cmp_lt_u32 s15, s13
	s_cbranch_scc0 .Lp2_ld6
	s_add_i32 s2, s12, -3
	s_mul_i32 s2, s2, 0x3400
	s_add_u32 s2, s2, 0x1800
	v_add_u32_e32 v246, s2, v244
	global_load_dwordx4 v[46:49], v246, s[4:5]
.Lp2_ld6:
	s_add_i32 s15, s14, -2
	s_cmp_lt_u32 s15, s13
	s_cbranch_scc0 .Lp2_ld7
	s_add_i32 s2, s12, -2
	s_mul_i32 s2, s2, 0x3400
	s_add_u32 s2, s2, 0x1800
	v_add_u32_e32 v246, s2, v244
	global_load_dwordx4 v[54:57], v246, s[4:5]
.Lp2_ld7:
	s_add_i32 s15, s14, -1
	s_cmp_lt_u32 s15, s13
	s_cbranch_scc0 .Lp2_ld8
	s_add_i32 s2, s12, -1
	s_mul_i32 s2, s2, 0x3400
	s_add_u32 s2, s2, 0x1800
	v_add_u32_e32 v246, s2, v244
	global_load_dwordx4 v[62:65], v246, s[4:5]
.Lp2_ld8:
	s_add_i32 s15, s14, 0
	s_cmp_lt_u32 s15, s13
	s_cbranch_scc0 .Lp2_ld9
	s_add_i32 s2, s12, 0
	s_mul_i32 s2, s2, 0x3400
	s_add_u32 s2, s2, 0x1800
	v_add_u32_e32 v246, s2, v244
	global_load_dwordx4 v[70:73], v246, s[4:5]
.Lp2_ld9:
	s_add_i32 s15, s14, 1
	s_cmp_lt_u32 s15, s13
	s_cbranch_scc0 .Lp2_ld10
	s_add_i32 s2, s12, 1
	s_mul_i32 s2, s2, 0x3400
	s_add_u32 s2, s2, 0x1800
	v_add_u32_e32 v246, s2, v244
	global_load_dwordx4 v[78:81], v246, s[4:5]
.Lp2_ld10:
	s_add_i32 s15, s14, 2
	s_cmp_lt_u32 s15, s13
	s_cbranch_scc0 .Lp2_ld11
	s_add_i32 s2, s12, 2
	s_mul_i32 s2, s2, 0x3400
	s_add_u32 s2, s2, 0x1800
	v_add_u32_e32 v246, s2, v244
	global_load_dwordx4 v[86:89], v246, s[4:5]
.Lp2_ld11:
	s_add_i32 s15, s14, 3
	s_cmp_lt_u32 s15, s13
	s_cbranch_scc0 .Lp2_ld12
	s_add_i32 s2, s12, 3
	s_mul_i32 s2, s2, 0x3400
	s_add_u32 s2, s2, 0x1800
	v_add_u32_e32 v246, s2, v244
	global_load_dwordx4 v[94:97], v246, s[4:5]
.Lp2_ld12:
	s_add_i32 s15, s14, 4
	s_cmp_lt_u32 s15, s13
	s_cbranch_scc0 .Lp2_ld13
	s_add_i32 s2, s12, 4
	s_mul_i32 s2, s2, 0x3400
	s_add_u32 s2, s2, 0x1800
	v_add_u32_e32 v246, s2, v244
	global_load_dwordx4 v[102:105], v246, s[4:5]
.Lp2_ld13:
	s_add_i32 s15, s14, 5
	s_cmp_lt_u32 s15, s13
	s_cbranch_scc0 .Lp2_ld14
	s_add_i32 s2, s12, 5
	s_mul_i32 s2, s2, 0x3400
	s_add_u32 s2, s2, 0x1800
	v_add_u32_e32 v246, s2, v244
	global_load_dwordx4 v[110:113], v246, s[4:5]
.Lp2_ld14:
	s_add_i32 s15, s14, 6
	s_cmp_lt_u32 s15, s13
	s_cbranch_scc0 .Lp2_ld15
	s_add_i32 s2, s12, 6
	s_mul_i32 s2, s2, 0x3400
	s_add_u32 s2, s2, 0x1800
	v_add_u32_e32 v246, s2, v244
	global_load_dwordx4 v[118:121], v246, s[4:5]
.Lp2_ld15:
	s_add_i32 s15, s14, 7
	s_cmp_lt_u32 s15, s13
	s_cbranch_scc0 .Lp2_ld16
	s_add_i32 s2, s12, 7
	s_mul_i32 s2, s2, 0x3400
	s_add_u32 s2, s2, 0x1800
	v_add_u32_e32 v246, s2, v244
	global_load_dwordx4 v[126:129], v246, s[4:5]
.Lp2_ld16:
	s_add_i32 s15, s14, 8
	s_cmp_lt_u32 s15, s13
	s_cbranch_scc0 .Lp2_ld17
	s_add_i32 s2, s12, 8
	s_mul_i32 s2, s2, 0x3400
	s_add_u32 s2, s2, 0x1800
	v_add_u32_e32 v246, s2, v244
	global_load_dwordx4 v[134:137], v246, s[4:5]
.Lp2_ld17:
	s_add_i32 s15, s14, 9
	s_cmp_lt_u32 s15, s13
	s_cbranch_scc0 .Lp2_ld18
	s_add_i32 s2, s12, 9
	s_mul_i32 s2, s2, 0x3400
	s_add_u32 s2, s2, 0x1800
	v_add_u32_e32 v246, s2, v244
	global_load_dwordx4 v[142:145], v246, s[4:5]
.Lp2_ld18:
	s_add_i32 s15, s14, 10
	s_cmp_lt_u32 s15, s13
	s_cbranch_scc0 .Lp2_ld19
	s_add_i32 s2, s12, 10
	s_mul_i32 s2, s2, 0x3400
	s_add_u32 s2, s2, 0x1800
	v_add_u32_e32 v246, s2, v244
	global_load_dwordx4 v[150:153], v246, s[4:5]
.Lp2_ld19:
	s_waitcnt vmcnt(0)
	v_lshlrev_b32_e32 v2, 16, v6
	v_and_b32_e32 v3, 0xffff0000, v6
	v_lshlrev_b32_e32 v4, 16, v7
	v_and_b32_e32 v5, 0xffff0000, v7
	v_lshlrev_b32_e32 v6, 16, v8
	v_and_b32_e32 v7, 0xffff0000, v8
	v_lshlrev_b32_e32 v8, 16, v9
	v_and_b32_e32 v9, 0xffff0000, v9
	v_lshlrev_b32_e32 v10, 16, v14
	v_and_b32_e32 v11, 0xffff0000, v14
	v_lshlrev_b32_e32 v12, 16, v15
	v_and_b32_e32 v13, 0xffff0000, v15
	v_lshlrev_b32_e32 v14, 16, v16
	v_and_b32_e32 v15, 0xffff0000, v16
	v_lshlrev_b32_e32 v16, 16, v17
	v_and_b32_e32 v17, 0xffff0000, v17
	v_lshlrev_b32_e32 v18, 16, v22
	v_and_b32_e32 v19, 0xffff0000, v22
	v_lshlrev_b32_e32 v20, 16, v23
	v_and_b32_e32 v21, 0xffff0000, v23
	v_lshlrev_b32_e32 v22, 16, v24
	v_and_b32_e32 v23, 0xffff0000, v24
	v_lshlrev_b32_e32 v24, 16, v25
	v_and_b32_e32 v25, 0xffff0000, v25
	v_lshlrev_b32_e32 v26, 16, v30
	v_and_b32_e32 v27, 0xffff0000, v30
	v_lshlrev_b32_e32 v28, 16, v31
	v_and_b32_e32 v29, 0xffff0000, v31
	v_lshlrev_b32_e32 v30, 16, v32
	v_and_b32_e32 v31, 0xffff0000, v32
	v_lshlrev_b32_e32 v32, 16, v33
	v_and_b32_e32 v33, 0xffff0000, v33
	v_lshlrev_b32_e32 v34, 16, v38
	v_and_b32_e32 v35, 0xffff0000, v38
	v_lshlrev_b32_e32 v36, 16, v39
	v_and_b32_e32 v37, 0xffff0000, v39
	v_lshlrev_b32_e32 v38, 16, v40
	v_and_b32_e32 v39, 0xffff0000, v40
	v_lshlrev_b32_e32 v40, 16, v41
	v_and_b32_e32 v41, 0xffff0000, v41
	v_lshlrev_b32_e32 v42, 16, v46
	v_and_b32_e32 v43, 0xffff0000, v46
	v_lshlrev_b32_e32 v44, 16, v47
	v_and_b32_e32 v45, 0xffff0000, v47
	v_lshlrev_b32_e32 v46, 16, v48
	v_and_b32_e32 v47, 0xffff0000, v48
	v_lshlrev_b32_e32 v48, 16, v49
	v_and_b32_e32 v49, 0xffff0000, v49
	v_lshlrev_b32_e32 v50, 16, v54
	v_and_b32_e32 v51, 0xffff0000, v54
	v_lshlrev_b32_e32 v52, 16, v55
	v_and_b32_e32 v53, 0xffff0000, v55
	v_lshlrev_b32_e32 v54, 16, v56
	v_and_b32_e32 v55, 0xffff0000, v56
	v_lshlrev_b32_e32 v56, 16, v57
	v_and_b32_e32 v57, 0xffff0000, v57
	v_lshlrev_b32_e32 v58, 16, v62
	v_and_b32_e32 v59, 0xffff0000, v62
	v_lshlrev_b32_e32 v60, 16, v63
	v_and_b32_e32 v61, 0xffff0000, v63
	v_lshlrev_b32_e32 v62, 16, v64
	v_and_b32_e32 v63, 0xffff0000, v64
	v_lshlrev_b32_e32 v64, 16, v65
	v_and_b32_e32 v65, 0xffff0000, v65
	v_lshlrev_b32_e32 v66, 16, v70
	v_and_b32_e32 v67, 0xffff0000, v70
	v_lshlrev_b32_e32 v68, 16, v71
	v_and_b32_e32 v69, 0xffff0000, v71
	v_lshlrev_b32_e32 v70, 16, v72
	v_and_b32_e32 v71, 0xffff0000, v72
	v_lshlrev_b32_e32 v72, 16, v73
	v_and_b32_e32 v73, 0xffff0000, v73
	v_lshlrev_b32_e32 v74, 16, v78
	v_and_b32_e32 v75, 0xffff0000, v78
	v_lshlrev_b32_e32 v76, 16, v79
	v_and_b32_e32 v77, 0xffff0000, v79
	v_lshlrev_b32_e32 v78, 16, v80
	v_and_b32_e32 v79, 0xffff0000, v80
	v_lshlrev_b32_e32 v80, 16, v81
	v_and_b32_e32 v81, 0xffff0000, v81
	v_lshlrev_b32_e32 v82, 16, v86
	v_and_b32_e32 v83, 0xffff0000, v86
	v_lshlrev_b32_e32 v84, 16, v87
	v_and_b32_e32 v85, 0xffff0000, v87
	v_lshlrev_b32_e32 v86, 16, v88
	v_and_b32_e32 v87, 0xffff0000, v88
	v_lshlrev_b32_e32 v88, 16, v89
	v_and_b32_e32 v89, 0xffff0000, v89
	v_lshlrev_b32_e32 v90, 16, v94
	v_and_b32_e32 v91, 0xffff0000, v94
	v_lshlrev_b32_e32 v92, 16, v95
	v_and_b32_e32 v93, 0xffff0000, v95
	v_lshlrev_b32_e32 v94, 16, v96
	v_and_b32_e32 v95, 0xffff0000, v96
	v_lshlrev_b32_e32 v96, 16, v97
	v_and_b32_e32 v97, 0xffff0000, v97
	v_lshlrev_b32_e32 v98, 16, v102
	v_and_b32_e32 v99, 0xffff0000, v102
	v_lshlrev_b32_e32 v100, 16, v103
	v_and_b32_e32 v101, 0xffff0000, v103
	v_lshlrev_b32_e32 v102, 16, v104
	v_and_b32_e32 v103, 0xffff0000, v104
	v_lshlrev_b32_e32 v104, 16, v105
	v_and_b32_e32 v105, 0xffff0000, v105
	v_lshlrev_b32_e32 v106, 16, v110
	v_and_b32_e32 v107, 0xffff0000, v110
	v_lshlrev_b32_e32 v108, 16, v111
	v_and_b32_e32 v109, 0xffff0000, v111
	v_lshlrev_b32_e32 v110, 16, v112
	v_and_b32_e32 v111, 0xffff0000, v112
	v_lshlrev_b32_e32 v112, 16, v113
	v_and_b32_e32 v113, 0xffff0000, v113
	v_lshlrev_b32_e32 v114, 16, v118
	v_and_b32_e32 v115, 0xffff0000, v118
	v_lshlrev_b32_e32 v116, 16, v119
	v_and_b32_e32 v117, 0xffff0000, v119
	v_lshlrev_b32_e32 v118, 16, v120
	v_and_b32_e32 v119, 0xffff0000, v120
	v_lshlrev_b32_e32 v120, 16, v121
	v_and_b32_e32 v121, 0xffff0000, v121
	v_lshlrev_b32_e32 v122, 16, v126
	v_and_b32_e32 v123, 0xffff0000, v126
	v_lshlrev_b32_e32 v124, 16, v127
	v_and_b32_e32 v125, 0xffff0000, v127
	v_lshlrev_b32_e32 v126, 16, v128
	v_and_b32_e32 v127, 0xffff0000, v128
	v_lshlrev_b32_e32 v128, 16, v129
	v_and_b32_e32 v129, 0xffff0000, v129
	v_lshlrev_b32_e32 v130, 16, v134
	v_and_b32_e32 v131, 0xffff0000, v134
	v_lshlrev_b32_e32 v132, 16, v135
	v_and_b32_e32 v133, 0xffff0000, v135
	v_lshlrev_b32_e32 v134, 16, v136
	v_and_b32_e32 v135, 0xffff0000, v136
	v_lshlrev_b32_e32 v136, 16, v137
	v_and_b32_e32 v137, 0xffff0000, v137
	v_lshlrev_b32_e32 v138, 16, v142
	v_and_b32_e32 v139, 0xffff0000, v142
	v_lshlrev_b32_e32 v140, 16, v143
	v_and_b32_e32 v141, 0xffff0000, v143
	v_lshlrev_b32_e32 v142, 16, v144
	v_and_b32_e32 v143, 0xffff0000, v144
	v_lshlrev_b32_e32 v144, 16, v145
	v_and_b32_e32 v145, 0xffff0000, v145
	v_lshlrev_b32_e32 v146, 16, v150
	v_and_b32_e32 v147, 0xffff0000, v150
	v_lshlrev_b32_e32 v148, 16, v151
	v_and_b32_e32 v149, 0xffff0000, v151
	v_lshlrev_b32_e32 v150, 16, v152
	v_and_b32_e32 v151, 0xffff0000, v152
	v_lshlrev_b32_e32 v152, 16, v153
	v_and_b32_e32 v153, 0xffff0000, v153
	v_mov_b32_e32 v212, 0
	v_mov_b32_e32 v213, 0
	v_mov_b32_e32 v214, 0
	v_mov_b32_e32 v215, 0
	v_mov_b32_e32 v216, 0
	v_mov_b32_e32 v217, 0
	v_mov_b32_e32 v218, 0
	v_mov_b32_e32 v219, 0
	s_add_i32 s15, s14, -8
	s_cmp_lt_u32 s15, s13
	s_cbranch_scc0 .Lp2_rw20
	s_mov_b64 exec, s[38:39]
	v_pk_add_f32 v[212:213], v[212:213], v[2:3]
	v_pk_add_f32 v[214:215], v[214:215], v[4:5]
	v_pk_add_f32 v[216:217], v[216:217], v[6:7]
	v_pk_add_f32 v[218:219], v[218:219], v[8:9]
.Lp2_rw20:
	s_add_i32 s15, s14, -7
	s_cmp_lt_u32 s15, s13
	s_cbranch_scc0 .Lp2_rw21
	s_mov_b64 exec, s[38:39]
	v_pk_add_f32 v[212:213], v[212:213], v[10:11]
	v_pk_add_f32 v[214:215], v[214:215], v[12:13]
	v_pk_add_f32 v[216:217], v[216:217], v[14:15]
	v_pk_add_f32 v[218:219], v[218:219], v[16:17]
.Lp2_rw21:
	s_add_i32 s15, s14, -6
	s_cmp_lt_u32 s15, s13
	s_cbranch_scc0 .Lp2_rw22
	s_mov_b64 exec, s[38:39]
	v_pk_add_f32 v[212:213], v[212:213], v[18:19]
	v_pk_add_f32 v[214:215], v[214:215], v[20:21]
	v_pk_add_f32 v[216:217], v[216:217], v[22:23]
	v_pk_add_f32 v[218:219], v[218:219], v[24:25]
.Lp2_rw22:
	s_add_i32 s15, s14, -5
	s_cmp_lt_u32 s15, s13
	s_cbranch_scc0 .Lp2_rw23
	s_mov_b64 exec, s[38:39]
	v_pk_add_f32 v[212:213], v[212:213], v[26:27]
	v_pk_add_f32 v[214:215], v[214:215], v[28:29]
	v_pk_add_f32 v[216:217], v[216:217], v[30:31]
	v_pk_add_f32 v[218:219], v[218:219], v[32:33]
.Lp2_rw23:
	s_add_i32 s15, s14, -4
	s_cmp_lt_u32 s15, s13
	s_cbranch_scc0 .Lp2_rw24
	s_mov_b64 exec, s[10:11]
	v_pk_add_f32 v[212:213], v[212:213], v[34:35]
	v_pk_add_f32 v[214:215], v[214:215], v[36:37]
	v_pk_add_f32 v[216:217], v[216:217], v[38:39]
	v_pk_add_f32 v[218:219], v[218:219], v[40:41]
.Lp2_rw24:
	s_add_i32 s15, s14, -3
	s_cmp_lt_u32 s15, s13
	s_cbranch_scc0 .Lp2_rw25
	s_mov_b64 exec, s[10:11]
	v_pk_add_f32 v[212:213], v[212:213], v[42:43]
	v_pk_add_f32 v[214:215], v[214:215], v[44:45]
	v_pk_add_f32 v[216:217], v[216:217], v[46:47]
	v_pk_add_f32 v[218:219], v[218:219], v[48:49]
.Lp2_rw25:
	s_add_i32 s15, s14, -2
	s_cmp_lt_u32 s15, s13
	s_cbranch_scc0 .Lp2_rw26
	s_mov_b64 exec, s[8:9]
	v_pk_add_f32 v[212:213], v[212:213], v[50:51]
	v_pk_add_f32 v[214:215], v[214:215], v[52:53]
	v_pk_add_f32 v[216:217], v[216:217], v[54:55]
	v_pk_add_f32 v[218:219], v[218:219], v[56:57]
.Lp2_rw26:
	s_add_i32 s15, s14, -1
	s_cmp_lt_u32 s15, s13
	s_cbranch_scc0 .Lp2_rw27
	s_mov_b64 exec, -1
	v_pk_add_f32 v[212:213], v[212:213], v[58:59]
	v_pk_add_f32 v[214:215], v[214:215], v[60:61]
	v_pk_add_f32 v[216:217], v[216:217], v[62:63]
	v_pk_add_f32 v[218:219], v[218:219], v[64:65]
.Lp2_rw27:
	s_add_i32 s15, s14, 0
	s_cmp_lt_u32 s15, s13
	s_cbranch_scc0 .Lp2_rw28
	s_mov_b64 exec, -1
	v_pk_add_f32 v[212:213], v[212:213], v[66:67]
	v_pk_add_f32 v[214:215], v[214:215], v[68:69]
	v_pk_add_f32 v[216:217], v[216:217], v[70:71]
	v_pk_add_f32 v[218:219], v[218:219], v[72:73]
.Lp2_rw28:
	s_add_i32 s15, s14, 1
	s_cmp_lt_u32 s15, s13
	s_cbranch_scc0 .Lp2_rw29
	s_mov_b64 exec, s[8:9]
	v_pk_add_f32 v[212:213], v[212:213], v[74:75]
	v_pk_add_f32 v[214:215], v[214:215], v[76:77]
	v_pk_add_f32 v[216:217], v[216:217], v[78:79]
	v_pk_add_f32 v[218:219], v[218:219], v[80:81]
.Lp2_rw29:
	s_add_i32 s15, s14, 2
	s_cmp_lt_u32 s15, s13
	s_cbranch_scc0 .Lp2_rw30
	s_mov_b64 exec, s[10:11]
	v_pk_add_f32 v[212:213], v[212:213], v[82:83]
	v_pk_add_f32 v[214:215], v[214:215], v[84:85]
	v_pk_add_f32 v[216:217], v[216:217], v[86:87]
	v_pk_add_f32 v[218:219], v[218:219], v[88:89]
.Lp2_rw30:
	s_add_i32 s15, s14, 3
	s_cmp_lt_u32 s15, s13
	s_cbranch_scc0 .Lp2_rw31
	s_mov_b64 exec, s[10:11]
	v_pk_add_f32 v[212:213], v[212:213], v[90:91]
	v_pk_add_f32 v[214:215], v[214:215], v[92:93]
	v_pk_add_f32 v[216:217], v[216:217], v[94:95]
	v_pk_add_f32 v[218:219], v[218:219], v[96:97]
.Lp2_rw31:
	s_add_i32 s15, s14, 4
	s_cmp_lt_u32 s15, s13
	s_cbranch_scc0 .Lp2_rw32
	s_mov_b64 exec, s[38:39]
	v_pk_add_f32 v[212:213], v[212:213], v[98:99]
	v_pk_add_f32 v[214:215], v[214:215], v[100:101]
	v_pk_add_f32 v[216:217], v[216:217], v[102:103]
	v_pk_add_f32 v[218:219], v[218:219], v[104:105]
.Lp2_rw32:
	s_add_i32 s15, s14, 5
	s_cmp_lt_u32 s15, s13
	s_cbranch_scc0 .Lp2_rw33
	s_mov_b64 exec, s[38:39]
	v_pk_add_f32 v[212:213], v[212:213], v[106:107]
	v_pk_add_f32 v[214:215], v[214:215], v[108:109]
	v_pk_add_f32 v[216:217], v[216:217], v[110:111]
	v_pk_add_f32 v[218:219], v[218:219], v[112:113]
.Lp2_rw33:
	s_add_i32 s15, s14, 6
	s_cmp_lt_u32 s15, s13
	s_cbranch_scc0 .Lp2_rw34
	s_mov_b64 exec, s[38:39]
	v_pk_add_f32 v[212:213], v[212:213], v[114:115]
	v_pk_add_f32 v[214:215], v[214:215], v[116:117]
	v_pk_add_f32 v[216:217], v[216:217], v[118:119]
	v_pk_add_f32 v[218:219], v[218:219], v[120:121]
.Lp2_rw34:
	s_add_i32 s15, s14, 7
	s_cmp_lt_u32 s15, s13
	s_cbranch_scc0 .Lp2_rw35
	s_mov_b64 exec, s[38:39]
	v_pk_add_f32 v[212:213], v[212:213], v[122:123]
	v_pk_add_f32 v[214:215], v[214:215], v[124:125]
	v_pk_add_f32 v[216:217], v[216:217], v[126:127]
	v_pk_add_f32 v[218:219], v[218:219], v[128:129]
.Lp2_rw35:
	s_mov_b64 exec, -1
	s_add_i32 s15, s14, 0
	v_sub_u32_e32 v247, s15, v245
	v_max_i32_e32 v247, 0, v247
	v_add_u32_e32 v248, s15, v245
	v_min_i32_e32 v248, s13, v248
	v_sub_u32_e32 v249, v248, v247
	v_cvt_f32_i32_e32 v154, v249
	v_div_scale_f32 v155, s[2:3], v154, v154, 1.0
	v_rcp_f32_e32 v156, v155
	s_nop 0
	v_fma_f32 v157, -v155, v156, 1.0
	v_fmac_f32_e32 v156, v157, v156
	v_div_scale_f32 v157, vcc, 1.0, v154, 1.0
	v_mul_f32_e32 v158, v157, v156
	v_fma_f32 v159, -v155, v158, v157
	v_fmac_f32_e32 v158, v159, v156
	v_fma_f32 v157, -v155, v158, v157
	s_nop 1
	v_div_fmas_f32 v157, v157, v156, v158
	v_div_fixup_f32 v157, v157, v154, 1.0
	v_mov_b32_e32 v156, v157
	v_pk_fma_f32 v[212:213], v[156:157], v[212:213], v[66:67] op_sel_hi:[0,1,1] neg_lo:[0,0,1] neg_hi:[0,0,1]
	v_pk_fma_f32 v[214:215], v[156:157], v[214:215], v[68:69] op_sel_hi:[0,1,1] neg_lo:[0,0,1] neg_hi:[0,0,1]
	v_pk_fma_f32 v[216:217], v[156:157], v[216:217], v[70:71] op_sel_hi:[0,1,1] neg_lo:[0,0,1] neg_hi:[0,0,1]
	v_pk_fma_f32 v[218:219], v[156:157], v[218:219], v[72:73] op_sel_hi:[0,1,1] neg_lo:[0,0,1] neg_hi:[0,0,1]
	s_nop 0
	v_cvt_pk_bf16_f32 v220, v212, v213
	v_cvt_pk_bf16_f32 v221, v214, v215
	v_cvt_pk_bf16_f32 v222, v216, v217
	v_cvt_pk_bf16_f32 v223, v218, v219
	s_add_u32 s2, s12, 0
	s_mul_i32 s2, s2, 0xc00
	v_add_u32_e32 v246, s2, v244
	global_store_dwordx4 v246, v[220:223], s[36:37] offset:2048
	v_mov_b32_e32 v212, 0
	v_mov_b32_e32 v213, 0
	v_mov_b32_e32 v214, 0
	v_mov_b32_e32 v215, 0
	v_mov_b32_e32 v216, 0
	v_mov_b32_e32 v217, 0
	v_mov_b32_e32 v218, 0
	v_mov_b32_e32 v219, 0
	s_add_i32 s15, s14, -7
	s_cmp_lt_u32 s15, s13
	s_cbranch_scc0 .Lp2_rw36
	s_mov_b64 exec, s[38:39]
	v_pk_add_f32 v[212:213], v[212:213], v[10:11]
	v_pk_add_f32 v[214:215], v[214:215], v[12:13]
	v_pk_add_f32 v[216:217], v[216:217], v[14:15]
	v_pk_add_f32 v[218:219], v[218:219], v[16:17]

.Lp2_rw38:
	s_add_i32 s15, s14, -4
	s_cmp_lt_u32 s15, s13
	s_cbranch_scc0 .Lp2_rw39
	s_mov_b64 exec, s[38:39]
	v_pk_add_f32 v[212:213], v[212:213], v[34:35]
	v_pk_add_f32 v[214:215], v[214:215], v[36:37]
	v_pk_add_f32 v[216:217], v[216:217], v[38:39]
	v_pk_add_f32 v[218:219], v[218:219], v[40:41]

.Lp2_rw40:
	s_add_i32 s15, s14, -2
	s_cmp_lt_u32 s15, s13
	s_cbranch_scc0 .Lp2_rw41
	s_mov_b64 exec, s[10:11]
	v_pk_add_f32 v[212:213], v[212:213], v[50:51]
	v_pk_add_f32 v[214:215], v[214:215], v[52:53]
	v_pk_add_f32 v[216:217], v[216:217], v[54:55]
	v_pk_add_f32 v[218:219], v[218:219], v[56:57]
.Lp2_rw41:
	s_add_i32 s15, s14, -1
	s_cmp_lt_u32 s15, s13
	s_cbranch_scc0 .Lp2_rw42
	s_mov_b64 exec, s[8:9]
	v_pk_add_f32 v[212:213], v[212:213], v[58:59]
	v_pk_add_f32 v[214:215], v[214:215], v[60:61]
	v_pk_add_f32 v[216:217], v[216:217], v[62:63]
	v_pk_add_f32 v[218:219], v[218:219], v[64:65]

.Lp2_rw43:
	s_add_i32 s15, s14, 1
	s_cmp_lt_u32 s15, s13
	s_cbranch_scc0 .Lp2_rw44
	s_mov_b64 exec, -1
	v_pk_add_f32 v[212:213], v[212:213], v[74:75]
	v_pk_add_f32 v[214:215], v[214:215], v[76:77]
	v_pk_add_f32 v[216:217], v[216:217], v[78:79]
	v_pk_add_f32 v[218:219], v[218:219], v[80:81]
.Lp2_rw44:
	s_add_i32 s15, s14, 2
	s_cmp_lt_u32 s15, s13
	s_cbranch_scc0 .Lp2_rw45
	s_mov_b64 exec, s[8:9]
	v_pk_add_f32 v[212:213], v[212:213], v[82:83]
	v_pk_add_f32 v[214:215], v[214:215], v[84:85]
	v_pk_add_f32 v[216:217], v[216:217], v[86:87]
	v_pk_add_f32 v[218:219], v[218:219], v[88:89]

.Lp2_rw46:
	s_add_i32 s15, s14, 4
	s_cmp_lt_u32 s15, s13
	s_cbranch_scc0 .Lp2_rw47
	s_mov_b64 exec, s[10:11]
	v_pk_add_f32 v[212:213], v[212:213], v[98:99]
	v_pk_add_f32 v[214:215], v[214:215], v[100:101]
	v_pk_add_f32 v[216:217], v[216:217], v[102:103]
	v_pk_add_f32 v[218:219], v[218:219], v[104:105]

.Lp2_rw50:
	s_add_i32 s15, s14, 8
	s_cmp_lt_u32 s15, s13
	s_cbranch_scc0 .Lp2_rw51
	s_mov_b64 exec, s[38:39]
	v_pk_add_f32 v[212:213], v[212:213], v[130:131]
	v_pk_add_f32 v[214:215], v[214:215], v[132:133]
	v_pk_add_f32 v[216:217], v[216:217], v[134:135]
	v_pk_add_f32 v[218:219], v[218:219], v[136:137]
.Lp2_rw51:
	s_mov_b64 exec, -1
	s_add_i32 s15, s14, 1
	v_sub_u32_e32 v247, s15, v245
	v_max_i32_e32 v247, 0, v247
	v_add_u32_e32 v248, s15, v245
	v_min_i32_e32 v248, s13, v248
	v_sub_u32_e32 v249, v248, v247
	v_cvt_f32_i32_e32 v154, v249
	v_div_scale_f32 v155, s[2:3], v154, v154, 1.0
	v_rcp_f32_e32 v156, v155
	s_nop 0
	v_fma_f32 v157, -v155, v156, 1.0
	v_fmac_f32_e32 v156, v157, v156
	v_div_scale_f32 v157, vcc, 1.0, v154, 1.0
	v_mul_f32_e32 v158, v157, v156
	v_fma_f32 v159, -v155, v158, v157
	v_fmac_f32_e32 v158, v159, v156
	v_fma_f32 v157, -v155, v158, v157
	s_nop 1
	v_div_fmas_f32 v157, v157, v156, v158
	v_div_fixup_f32 v157, v157, v154, 1.0
	v_mov_b32_e32 v156, v157
	v_pk_fma_f32 v[212:213], v[156:157], v[212:213], v[74:75] op_sel_hi:[0,1,1] neg_lo:[0,0,1] neg_hi:[0,0,1]
	v_pk_fma_f32 v[214:215], v[156:157], v[214:215], v[76:77] op_sel_hi:[0,1,1] neg_lo:[0,0,1] neg_hi:[0,0,1]
	v_pk_fma_f32 v[216:217], v[156:157], v[216:217], v[78:79] op_sel_hi:[0,1,1] neg_lo:[0,0,1] neg_hi:[0,0,1]
	v_pk_fma_f32 v[218:219], v[156:157], v[218:219], v[80:81] op_sel_hi:[0,1,1] neg_lo:[0,0,1] neg_hi:[0,0,1]
	s_nop 0
	v_cvt_pk_bf16_f32 v220, v212, v213
	v_cvt_pk_bf16_f32 v221, v214, v215
	v_cvt_pk_bf16_f32 v222, v216, v217
	v_cvt_pk_bf16_f32 v223, v218, v219
	s_add_u32 s2, s12, 1
	s_mul_i32 s2, s2, 0xc00
	v_add_u32_e32 v246, s2, v244
	global_store_dwordx4 v246, v[220:223], s[36:37] offset:2048
	v_mov_b32_e32 v212, 0
	v_mov_b32_e32 v213, 0
	v_mov_b32_e32 v214, 0
	v_mov_b32_e32 v215, 0
	v_mov_b32_e32 v216, 0
	v_mov_b32_e32 v217, 0
	v_mov_b32_e32 v218, 0
	v_mov_b32_e32 v219, 0
	s_add_i32 s15, s14, -6
	s_cmp_lt_u32 s15, s13
	s_cbranch_scc0 .Lp2_rw52
	s_mov_b64 exec, s[38:39]
	v_pk_add_f32 v[212:213], v[212:213], v[18:19]
	v_pk_add_f32 v[214:215], v[214:215], v[20:21]
	v_pk_add_f32 v[216:217], v[216:217], v[22:23]
	v_pk_add_f32 v[218:219], v[218:219], v[24:25]

.Lp2_rw54:
	s_add_i32 s15, s14, -3
	s_cmp_lt_u32 s15, s13
	s_cbranch_scc0 .Lp2_rw55
	s_mov_b64 exec, s[38:39]
	v_pk_add_f32 v[212:213], v[212:213], v[42:43]
	v_pk_add_f32 v[214:215], v[214:215], v[44:45]
	v_pk_add_f32 v[216:217], v[216:217], v[46:47]
	v_pk_add_f32 v[218:219], v[218:219], v[48:49]

.Lp2_rw56:
	s_add_i32 s15, s14, -1
	s_cmp_lt_u32 s15, s13
	s_cbranch_scc0 .Lp2_rw57
	s_mov_b64 exec, s[10:11]
	v_pk_add_f32 v[212:213], v[212:213], v[58:59]
	v_pk_add_f32 v[214:215], v[214:215], v[60:61]
	v_pk_add_f32 v[216:217], v[216:217], v[62:63]
	v_pk_add_f32 v[218:219], v[218:219], v[64:65]
.Lp2_rw57:
	s_add_i32 s15, s14, 0
	s_cmp_lt_u32 s15, s13
	s_cbranch_scc0 .Lp2_rw58
	s_mov_b64 exec, s[8:9]
	v_pk_add_f32 v[212:213], v[212:213], v[66:67]
	v_pk_add_f32 v[214:215], v[214:215], v[68:69]
	v_pk_add_f32 v[216:217], v[216:217], v[70:71]
	v_pk_add_f32 v[218:219], v[218:219], v[72:73]

.Lp2_rw59:
	s_add_i32 s15, s14, 2
	s_cmp_lt_u32 s15, s13
	s_cbranch_scc0 .Lp2_rw60
	s_mov_b64 exec, -1
	v_pk_add_f32 v[212:213], v[212:213], v[82:83]
	v_pk_add_f32 v[214:215], v[214:215], v[84:85]
	v_pk_add_f32 v[216:217], v[216:217], v[86:87]
	v_pk_add_f32 v[218:219], v[218:219], v[88:89]
.Lp2_rw60:
	s_add_i32 s15, s14, 3
	s_cmp_lt_u32 s15, s13
	s_cbranch_scc0 .Lp2_rw61
	s_mov_b64 exec, s[8:9]
	v_pk_add_f32 v[212:213], v[212:213], v[90:91]
	v_pk_add_f32 v[214:215], v[214:215], v[92:93]
	v_pk_add_f32 v[216:217], v[216:217], v[94:95]
	v_pk_add_f32 v[218:219], v[218:219], v[96:97]

.Lp2_rw62:
	s_add_i32 s15, s14, 5
	s_cmp_lt_u32 s15, s13
	s_cbranch_scc0 .Lp2_rw63
	s_mov_b64 exec, s[10:11]
	v_pk_add_f32 v[212:213], v[212:213], v[106:107]
	v_pk_add_f32 v[214:215], v[214:215], v[108:109]
	v_pk_add_f32 v[216:217], v[216:217], v[110:111]
	v_pk_add_f32 v[218:219], v[218:219], v[112:113]

.Lp2_rw66:
	s_add_i32 s15, s14, 9
	s_cmp_lt_u32 s15, s13
	s_cbranch_scc0 .Lp2_rw67
	s_mov_b64 exec, s[38:39]
	v_pk_add_f32 v[212:213], v[212:213], v[138:139]
	v_pk_add_f32 v[214:215], v[214:215], v[140:141]
	v_pk_add_f32 v[216:217], v[216:217], v[142:143]
	v_pk_add_f32 v[218:219], v[218:219], v[144:145]
.Lp2_rw67:
	s_mov_b64 exec, -1
	s_add_i32 s15, s14, 2
	v_sub_u32_e32 v247, s15, v245
	v_max_i32_e32 v247, 0, v247
	v_add_u32_e32 v248, s15, v245
	v_min_i32_e32 v248, s13, v248
	v_sub_u32_e32 v249, v248, v247
	v_cvt_f32_i32_e32 v154, v249
	v_div_scale_f32 v155, s[2:3], v154, v154, 1.0
	v_rcp_f32_e32 v156, v155
	s_nop 0
	v_fma_f32 v157, -v155, v156, 1.0
	v_fmac_f32_e32 v156, v157, v156
	v_div_scale_f32 v157, vcc, 1.0, v154, 1.0
	v_mul_f32_e32 v158, v157, v156
	v_fma_f32 v159, -v155, v158, v157
	v_fmac_f32_e32 v158, v159, v156
	v_fma_f32 v157, -v155, v158, v157
	s_nop 1
	v_div_fmas_f32 v157, v157, v156, v158
	v_div_fixup_f32 v157, v157, v154, 1.0
	v_mov_b32_e32 v156, v157
	v_pk_fma_f32 v[212:213], v[156:157], v[212:213], v[82:83] op_sel_hi:[0,1,1] neg_lo:[0,0,1] neg_hi:[0,0,1]
	v_pk_fma_f32 v[214:215], v[156:157], v[214:215], v[84:85] op_sel_hi:[0,1,1] neg_lo:[0,0,1] neg_hi:[0,0,1]
	v_pk_fma_f32 v[216:217], v[156:157], v[216:217], v[86:87] op_sel_hi:[0,1,1] neg_lo:[0,0,1] neg_hi:[0,0,1]
	v_pk_fma_f32 v[218:219], v[156:157], v[218:219], v[88:89] op_sel_hi:[0,1,1] neg_lo:[0,0,1] neg_hi:[0,0,1]
	s_nop 0
	v_cvt_pk_bf16_f32 v220, v212, v213
	v_cvt_pk_bf16_f32 v221, v214, v215
	v_cvt_pk_bf16_f32 v222, v216, v217
	v_cvt_pk_bf16_f32 v223, v218, v219
	s_add_u32 s2, s12, 2
	s_mul_i32 s2, s2, 0xc00
	v_add_u32_e32 v246, s2, v244
	global_store_dwordx4 v246, v[220:223], s[36:37] offset:2048
	v_mov_b32_e32 v212, 0
	v_mov_b32_e32 v213, 0
	v_mov_b32_e32 v214, 0
	v_mov_b32_e32 v215, 0
	v_mov_b32_e32 v216, 0
	v_mov_b32_e32 v217, 0
	v_mov_b32_e32 v218, 0
	v_mov_b32_e32 v219, 0
	s_add_i32 s15, s14, -5
	s_cmp_lt_u32 s15, s13
	s_cbranch_scc0 .Lp2_rw68
	s_mov_b64 exec, s[38:39]
	v_pk_add_f32 v[212:213], v[212:213], v[26:27]
	v_pk_add_f32 v[214:215], v[214:215], v[28:29]
	v_pk_add_f32 v[216:217], v[216:217], v[30:31]
	v_pk_add_f32 v[218:219], v[218:219], v[32:33]

.Lp2_rw70:
	s_add_i32 s15, s14, -2
	s_cmp_lt_u32 s15, s13
	s_cbranch_scc0 .Lp2_rw71
	s_mov_b64 exec, s[38:39]
	v_pk_add_f32 v[212:213], v[212:213], v[50:51]
	v_pk_add_f32 v[214:215], v[214:215], v[52:53]
	v_pk_add_f32 v[216:217], v[216:217], v[54:55]
	v_pk_add_f32 v[218:219], v[218:219], v[56:57]

.Lp2_rw72:
	s_add_i32 s15, s14, 0
	s_cmp_lt_u32 s15, s13
	s_cbranch_scc0 .Lp2_rw73
	s_mov_b64 exec, s[10:11]
	v_pk_add_f32 v[212:213], v[212:213], v[66:67]
	v_pk_add_f32 v[214:215], v[214:215], v[68:69]
	v_pk_add_f32 v[216:217], v[216:217], v[70:71]
	v_pk_add_f32 v[218:219], v[218:219], v[72:73]

.Lp2_rw75:
	s_add_i32 s15, s14, 3
	s_cmp_lt_u32 s15, s13
	s_cbranch_scc0 .Lp2_rw76
	s_mov_b64 exec, -1
	v_pk_add_f32 v[212:213], v[212:213], v[90:91]
	v_pk_add_f32 v[214:215], v[214:215], v[92:93]
	v_pk_add_f32 v[216:217], v[216:217], v[94:95]
	v_pk_add_f32 v[218:219], v[218:219], v[96:97]
.Lp2_rw76:
	s_add_i32 s15, s14, 4
	s_cmp_lt_u32 s15, s13
	s_cbranch_scc0 .Lp2_rw77
	s_mov_b64 exec, s[8:9]
	v_pk_add_f32 v[212:213], v[212:213], v[98:99]
	v_pk_add_f32 v[214:215], v[214:215], v[100:101]
	v_pk_add_f32 v[216:217], v[216:217], v[102:103]
	v_pk_add_f32 v[218:219], v[218:219], v[104:105]

.Lp2_rw78:
	s_add_i32 s15, s14, 6
	s_cmp_lt_u32 s15, s13
	s_cbranch_scc0 .Lp2_rw79
	s_mov_b64 exec, s[10:11]
	v_pk_add_f32 v[212:213], v[212:213], v[114:115]
	v_pk_add_f32 v[214:215], v[214:215], v[116:117]
	v_pk_add_f32 v[216:217], v[216:217], v[118:119]
	v_pk_add_f32 v[218:219], v[218:219], v[120:121]

.Lp2_rw82:
	s_add_i32 s15, s14, 10
	s_cmp_lt_u32 s15, s13
	s_cbranch_scc0 .Lp2_rw83
	s_mov_b64 exec, s[38:39]
	v_pk_add_f32 v[212:213], v[212:213], v[146:147]
	v_pk_add_f32 v[214:215], v[214:215], v[148:149]
	v_pk_add_f32 v[216:217], v[216:217], v[150:151]
	v_pk_add_f32 v[218:219], v[218:219], v[152:153]
.Lp2_rw83:
	s_mov_b64 exec, -1
	s_add_i32 s15, s14, 3
	v_sub_u32_e32 v247, s15, v245
	v_max_i32_e32 v247, 0, v247
	v_add_u32_e32 v248, s15, v245
	v_min_i32_e32 v248, s13, v248
	v_sub_u32_e32 v249, v248, v247
	v_cvt_f32_i32_e32 v154, v249
	v_div_scale_f32 v155, s[2:3], v154, v154, 1.0
	v_rcp_f32_e32 v156, v155
	s_nop 0
	v_fma_f32 v157, -v155, v156, 1.0
	v_fmac_f32_e32 v156, v157, v156
	v_div_scale_f32 v157, vcc, 1.0, v154, 1.0
	v_mul_f32_e32 v158, v157, v156
	v_fma_f32 v159, -v155, v158, v157
	v_fmac_f32_e32 v158, v159, v156
	v_fma_f32 v157, -v155, v158, v157
	s_nop 1
	v_div_fmas_f32 v157, v157, v156, v158
	v_div_fixup_f32 v157, v157, v154, 1.0
	v_mov_b32_e32 v156, v157
	v_pk_fma_f32 v[212:213], v[156:157], v[212:213], v[90:91] op_sel_hi:[0,1,1] neg_lo:[0,0,1] neg_hi:[0,0,1]
	v_pk_fma_f32 v[214:215], v[156:157], v[214:215], v[92:93] op_sel_hi:[0,1,1] neg_lo:[0,0,1] neg_hi:[0,0,1]
	v_pk_fma_f32 v[216:217], v[156:157], v[216:217], v[94:95] op_sel_hi:[0,1,1] neg_lo:[0,0,1] neg_hi:[0,0,1]
	v_pk_fma_f32 v[218:219], v[156:157], v[218:219], v[96:97] op_sel_hi:[0,1,1] neg_lo:[0,0,1] neg_hi:[0,0,1]
	s_nop 0
	v_cvt_pk_bf16_f32 v220, v212, v213
	v_cvt_pk_bf16_f32 v221, v214, v215
	v_cvt_pk_bf16_f32 v222, v216, v217
	v_cvt_pk_bf16_f32 v223, v218, v219
	s_add_u32 s2, s12, 3
	s_mul_i32 s2, s2, 0xc00
	v_add_u32_e32 v246, s2, v244
	global_store_dwordx4 v246, v[220:223], s[36:37] offset:2048
	s_branch .LBB0_403
